# v13 with F1 pool redistribution retuned: blocks 0-15 keep 6 pool items, 32 orphan items go to blocks 96-127
# speedup vs baseline: 1.0104x; 1.0101x over previous
; __device__ __forceinline__ void phase_f1(const Params& p, int l, char* sm) {
;   constexpr int NPOOL = (NBP * NCH + 16) * 4;
;   for (int it = blockIdx.x; it < NUNIT_P + NPOOL; it += gridDim.x) {
;     if (it < NUNIT_P) f1_unit(p, l, it, sm);
;     else pool_item(p, l, it - NUNIT_P, sm);
;   }
;   state_copies(p, l, blockIdx.x, gridDim.x);
; }
.LBB0_739:
	s_add_i32 s96, s96, s84
	s_cmpk_lg_u32 s84, 0x100
	s_cbranch_scc1 .Lf1bal0_std
	v_readlane_b32 s100, v247, 62
	s_nop 1
	s_cmp_lt_u32 s100, 16
	s_cbranch_scc0 .Lf1bal0_hi
	s_cmpk_lt_i32 s96, 0xf00
	s_cbranch_scc1 .Lf1bal0_cont
	s_branch .Lf1bal0_exit
.Lf1bal0_hi:
	s_cmpk_gt_i32 s96, 0x105f
	s_cbranch_scc0 .Lf1bal0_cont
	s_cmp_lg_u32 s101, 0
	s_cbranch_scc1 .Lf1bal0_exit
	s_sub_u32 s100, s100, 0x60
	s_cmp_lt_u32 s100, 32
	s_cbranch_scc0 .Lf1bal0_exit
	s_mov_b32 s101, 1
	s_lshr_b32 s96, s100, 4
	s_add_u32 s96, s96, 15
	s_lshl_b32 s96, s96, 8
	s_and_b32 s100, s100, 15
	s_add_u32 s96, s96, s100
	s_branch .Lf1bal0_cont

; __device__ __forceinline__ void phase_f1(const Params& p, int l, char* sm) {
;   constexpr int NPOOL = (NBP * NCH + 16) * 4;
;   for (int it = blockIdx.x; it < NUNIT_P + NPOOL; it += gridDim.x) {
;     if (it < NUNIT_P) f1_unit(p, l, it, sm);
;     else pool_item(p, l, it - NUNIT_P, sm);
;   }
;   state_copies(p, l, blockIdx.x, gridDim.x);
; }
.LBB0_3497:
	s_add_i32 s44, s44, s84
	s_cmpk_lg_u32 s84, 0x100
	s_cbranch_scc1 .Lf1bal1_std
	v_readlane_b32 s100, v247, 62
	s_nop 1
	s_cmp_lt_u32 s100, 16
	s_cbranch_scc0 .Lf1bal1_hi
	s_cmpk_lt_i32 s44, 0xf00
	s_cbranch_scc1 .Lf1bal1_cont
	s_branch .Lf1bal1_exit
.Lf1bal1_hi:
	s_cmpk_gt_i32 s44, 0x105f
	s_cbranch_scc0 .Lf1bal1_cont
	s_cmp_lg_u32 s101, 0
	s_cbranch_scc1 .Lf1bal1_exit
	s_sub_u32 s100, s100, 0x60
	s_cmp_lt_u32 s100, 32
	s_cbranch_scc0 .Lf1bal1_exit
	s_mov_b32 s101, 1
	s_lshr_b32 s44, s100, 4
	s_add_u32 s44, s44, 15
	s_lshl_b32 s44, s44, 8
	s_and_b32 s100, s100, 15
	s_add_u32 s44, s44, s100
	s_branch .Lf1bal1_cont
